# one static s_setprio 1 for waves 4-7 at kernel entry (timing-only), on top of v15
# speedup vs baseline: 1.0432x; 1.0013x over previous
; #define LAS __attribute__((address_space(3)))
; __device__ __forceinline__ unsigned xb_add(unsigned* p, unsigned v) { return __hip_atomic_fetch_add(p, v, __ATOMIC_RELAXED, __HIP_MEMORY_SCOPE_AGENT); }
; __device__ __forceinline__ unsigned xb_xcc_id() { return (unsigned)__builtin_amdgcn_s_getreg((3 << 11) | 20) & 0xFu; }
; __device__ __forceinline__ XcdBarrier xcd_barrier_post(unsigned* bar, volatile LAS unsigned* st) {
;     XcdBarrier b; b.bar = bar; b.x = xb_xcc_id(); b.st = st;
;     if (threadIdx.x == 0) (void)xb_add(&bar[XB_XCNT(b.x)], 1u);
;     return b;
; __global__ void __launch_bounds__(NTHREADS) fwd_megakernel(Params P) {
;     extern __shared__ __attribute__((aligned(16))) char lds[];
;     cg::grid_group grid = cg::this_grid();
;     __shared__ uint4 xb_words;
;     if (threadIdx.x == 0) xb_words = make_uint4(0u, 0u, 0u, 0u);
;     __syncthreads();
;     XcdBarrier xb = xcd_barrier_post((unsigned*)(P.ws + OFF_BAR), (volatile LAS unsigned*)&xb_words);
_Z14fwd_megakernel6Params:
	s_load_dwordx8 s[4:11], s[0:1], 0x80
	v_and_b32_e32 v200, 0x3ff, v0
	v_cmp_eq_u32_e64 s[44:45], 0, v200
	v_readfirstlane_b32 s3, v200
	s_nop 3
	s_cmpk_lt_u32 s3, 0x100
	s_cbranch_scc1 .Lprio_skip
	s_setprio 1
.Lprio_skip:
	s_waitcnt lgkmcnt(0)
	v_writelane_b32 v252, s4, 0
	s_nop 1
	v_writelane_b32 v252, s5, 1
	v_writelane_b32 v252, s6, 2
	v_writelane_b32 v252, s7, 3
	v_writelane_b32 v252, s8, 4
	v_writelane_b32 v252, s9, 5
	v_writelane_b32 v252, s10, 6
	v_writelane_b32 v252, s11, 7
	s_load_dwordx4 s[88:91], s[0:1], 0xa0
	s_load_dwordx2 s[4:5], s[0:1], 0xb0
	s_add_u32 s6, s0, 0xb0
	s_addc_u32 s7, s1, 0
	s_waitcnt lgkmcnt(0)
	v_writelane_b32 v252, s4, 8
	s_nop 1
	v_writelane_b32 v252, s5, 9
	s_and_saveexec_b64 s[4:5], s[44:45]
	v_mov_b32_e32 v2, 0
	v_mov_b32_e32 v3, v2
	v_mov_b32_e32 v4, v2
	v_mov_b32_e32 v5, v2
	ds_write_b128 v2, v[2:5]
	s_or_b64 exec, exec, s[4:5]
	s_load_dword s3, s[0:1], 0xb8
	s_add_u32 s4, s90, 0x1e699900
	s_addc_u32 s5, s91, 0
	s_waitcnt lgkmcnt(0)
	s_barrier
	v_writelane_b32 v252, s3, 10
	v_writelane_b32 v252, s4, 11
	s_getreg_b32 s3, hwreg(HW_REG_XCC_ID, 0, 4)
	s_and_b32 s3, s3, 15
	v_writelane_b32 v252, s5, 12
	v_writelane_b32 v252, s3, 13
	s_and_saveexec_b64 s[4:5], s[44:45]
	s_cbranch_execz .LBB0_5
	s_mov_b64 s[8:9], exec
	v_mbcnt_lo_u32_b32 v1, s8, 0
	v_mbcnt_hi_u32_b32 v1, s9, v1
	v_cmp_eq_u32_e32 vcc, 0, v1
	s_and_b64 s[10:11], exec, vcc
	s_mov_b64 exec, s[10:11]
	s_cbranch_execz .LBB0_5
	v_readlane_b32 s3, v252, 13
	s_bcnt1_i32_b64 s8, s[8:9]
	s_lshl_b32 s3, s3, 8
	v_mov_b32_e32 v2, s8
	v_readlane_b32 s8, v252, 11
	v_mov_b32_e32 v1, s3
	v_readlane_b32 s9, v252, 12
	s_nop 4
	global_atomic_add v1, v2, s[8:9] offset:1024
